# w_in QKV epilogue: next pair's rope rows loaded as soon as the current row block's rope registers die (fresh address temps), counted waits vmcnt(6)/(2)
# speedup vs baseline: 1.0069x; 1.0027x over previous
;   DI void operator()(const f32x4 (&acc)[2][2][4][2], const Unit& u, int wr, int wc, int fr, int fq) const {
;     ...
;           const int tt = u.pm * BM + ai * HALF + wr * 64 + (2 * mp + m2) * 16 + fr;
;           const float* rp = rope + (size_t)(tt & 4095) * 64 + 2 * (8 * fq);
; #pragma unroll
;           for (int n = 0; n < 2; ++n) { csr[m2][n][0] = *(const f32x4*)(rp + 8 * n); csr[m2][n][1] = *(const f32x4*)(rp + 8 * n + 4); }
;     ...
;           u16* dst = base + (size_t)pos * 64 + 8 * fq;
;           *(uint4*)(dst) = make_uint4(pack_bf16(o1[0], o1[1]), pack_bf16(o1[2], o1[3]), pack_bf16(o1[4], o1[5]), pack_bf16(o1[6], o1[7]));
;           *(uint4*)(dst + 32) = make_uint4(pack_bf16(o2[0], o2[1]), pack_bf16(o2[2], o2[3]), pack_bf16(o2[4], o2[5]), pack_bf16(o2[6], o2[7]));
.Lqkv_norope_0:
	v_mov_b32_e32 v240, s49
	v_and_b32_e32 v240, 0xfc0, v240
	v_or_b32_e32 v240, v240, v214
	v_add_u32_e32 v240, 0x20, v240
	v_lshlrev_b32_e32 v240, 8, v240
	v_mov_b32_e32 v241, 0
	v_lshl_add_u64 v[240:241], v[196:197], 0, v[240:241]
	global_load_dwordx4 v[126:129], v[240:241], off
	global_load_dwordx4 v[122:125], v[240:241], off offset:16
	global_load_dwordx4 v[118:121], v[240:241], off offset:32
	global_load_dwordx4 v[114:117], v[240:241], off offset:48
	v_lshlrev_b32_e32 v226, 7, v209
	v_mov_b32_e32 v227, v1
	v_lshl_add_u64 v[226:227], s[10:11], 0, v[226:227]
	v_mov_b32_e32 v207, v1
	v_lshl_add_u64 v[226:227], v[226:227], 0, v[206:207]
	v_cvt_pk_bf16_f32 v218, v218, v219
	v_cvt_pk_bf16_f32 v219, v220, v221
	v_cvt_pk_bf16_f32 v220, v222, v223
	v_cvt_pk_bf16_f32 v221, v224, v225
	global_store_dwordx4 v[226:227], v[218:221], off
	s_mov_b64 s[22:23], 0
	s_nop 0
	v_cvt_pk_bf16_f32 v218, v230, v231
	v_cvt_pk_bf16_f32 v219, v228, v229
	v_cvt_pk_bf16_f32 v220, v238, v239
	v_cvt_pk_bf16_f32 v221, v236, v237
	global_store_dwordx4 v[226:227], v[218:221], off offset:64

;   DI void operator()(const f32x4 (&acc)[2][2][4][2], const Unit& u, int wr, int wc, int fr, int fq) const {
;     ...
;           const int tt = u.pm * BM + ai * HALF + wr * 64 + (2 * mp + m2) * 16 + fr;
;           const float* rp = rope + (size_t)(tt & 4095) * 64 + 2 * (8 * fq);
; #pragma unroll
;           for (int n = 0; n < 2; ++n) { csr[m2][n][0] = *(const f32x4*)(rp + 8 * n); csr[m2][n][1] = *(const f32x4*)(rp + 8 * n + 4); }
;     ...
;           u16* dst = base + (size_t)pos * 64 + 8 * fq;
;           *(uint4*)(dst) = make_uint4(pack_bf16(o1[0], o1[1]), pack_bf16(o1[2], o1[3]), pack_bf16(o1[4], o1[5]), pack_bf16(o1[6], o1[7]));
;           *(uint4*)(dst + 32) = make_uint4(pack_bf16(o2[0], o2[1]), pack_bf16(o2[2], o2[3]), pack_bf16(o2[4], o2[5]), pack_bf16(o2[6], o2[7]));
.Lqkv_norope_1:
	v_mov_b32_e32 v240, s49
	v_and_b32_e32 v240, 0xfc0, v240
	v_or_b32_e32 v240, v240, v214
	v_add_u32_e32 v240, 0x30, v240
	v_lshlrev_b32_e32 v240, 8, v240
	v_mov_b32_e32 v241, 0
	v_lshl_add_u64 v[240:241], v[196:197], 0, v[240:241]
	global_load_dwordx4 v[94:97], v[240:241], off
	global_load_dwordx4 v[98:101], v[240:241], off offset:16
	global_load_dwordx4 v[86:89], v[240:241], off offset:32
	global_load_dwordx4 v[82:85], v[240:241], off offset:48
	v_mov_b32_e32 v207, v1
	v_lshlrev_b32_e32 v164, 7, v162
	v_mov_b32_e32 v165, v1
	v_lshl_add_u64 v[164:165], s[10:11], 0, v[164:165]
	v_lshl_add_u64 v[174:175], v[164:165], 0, v[206:207]
	v_cvt_pk_bf16_f32 v164, v166, v167
	v_cvt_pk_bf16_f32 v165, v168, v169
	v_cvt_pk_bf16_f32 v166, v170, v171
	v_cvt_pk_bf16_f32 v167, v172, v173
	global_store_dwordx4 v[174:175], v[164:167], off
	s_mov_b64 s[22:23], 0
	s_nop 0
	v_cvt_pk_bf16_f32 v164, v218, v219
	v_cvt_pk_bf16_f32 v165, v176, v177
	v_cvt_pk_bf16_f32 v166, v226, v227
	v_cvt_pk_bf16_f32 v167, v222, v223
	global_store_dwordx4 v[174:175], v[164:167], off offset:64

;   DI void operator()(const f32x4 (&acc)[2][2][4][2], const Unit& u, int wr, int wc, int fr, int fq) const {
;     ...
;           const int tt = u.pm * BM + ai * HALF + wr * 64 + (2 * mp + m2) * 16 + fr;
;           const float* rp = rope + (size_t)(tt & 4095) * 64 + 2 * (8 * fq);
; #pragma unroll
;           for (int n = 0; n < 2; ++n) { csr[m2][n][0] = *(const f32x4*)(rp + 8 * n); csr[m2][n][1] = *(const f32x4*)(rp + 8 * n + 4); }
;     ...
;           float ss = 0.f;
; #pragma unroll
;           for (int bj = 0; bj < 2; ++bj)
; #pragma unroll
;             for (int n = 0; n < 2; ++n)
; #pragma unroll
;               for (int e = 0; e < 4; ++e) ss += acc[ai][bj][m][n][e] * acc[ai][bj][m][n][e];
;           ss += __shfl_xor(ss, 16);
;           ss += __shfl_xor(ss, 32);
;           const float rinv = rsqrtf(ss * (1.f / 64.f) + EPSV);
;           float o1[8], o2[8];
; #pragma unroll
;           for (int n = 0; n < 2; ++n) {
;             f32x4 cs0 = (f32x4){1.f, 0.f, 1.f, 0.f}, cs1 = cs0;
;             if (ropeT) { cs0 = csr[m & 1][n][0]; cs1 = csr[m & 1][n][1]; }
; #pragma unroll
;             for (int e = 0; e < 4; ++e) {
;               float x1 = acc[ai][0][m][n][e] * (rinv * qs) * g4[0][n][e];
;               float x2 = acc[ai][1][m][n][e] * (rinv * qs) * g4[1][n][e];
;               float c = (e < 2) ? cs0[2 * e] : cs1[2 * (e - 2)], s = (e < 2) ? cs0[2 * e + 1] : cs1[2 * (e - 2) + 1];
;               o1[n * 4 + e] = x1 * c - x2 * s;
;               o2[n * 4 + e] = x2 * c + x1 * s;
;             }
;           }
;           u16* dst = base + (size_t)pos * 64 + 8 * fq;
;           *(uint4*)(dst) = make_uint4(pack_bf16(o1[0], o1[1]), pack_bf16(o1[2], o1[3]), pack_bf16(o1[4], o1[5]), pack_bf16(o1[6], o1[7]));
;           *(uint4*)(dst + 32) = make_uint4(pack_bf16(o2[0], o2[1]), pack_bf16(o2[2], o2[3]), pack_bf16(o2[4], o2[5]), pack_bf16(o2[6], o2[7]));
.LBB0_546:
	s_add_i32 s2, s50, s43
	s_and_b32 s3, s2, 0xfe0
	s_ashr_i32 s2, s2, 7
	s_andn2_b32 s2, s2, 31
	s_add_i32 s2, s2, s48
	v_or_b32_e32 v146, s3, v214
	s_mul_hi_i32 s3, s2, 0x88000
	s_mul_i32 s2, s2, 0x88000
	s_add_u32 s2, s88, s2
	s_addc_u32 s3, s89, s3
	s_and_b64 vcc, exec, s[8:9]
	s_mov_b64 s[22:23], -1
	s_cbranch_vccnz .LBB0_548
	v_mul_f32_e32 v0, v143, v143
	v_fmac_f32_e32 v0, v142, v142
	v_fmac_f32_e32 v0, v144, v144
	v_fmac_f32_e32 v0, v145, v145
	v_fmac_f32_e32 v0, v138, v138
	v_fmac_f32_e32 v0, v139, v139
	v_fmac_f32_e32 v0, v140, v140
	v_fmac_f32_e32 v0, v141, v141
	v_pk_mul_f32 v[150:151], v[134:135], v[134:135]
	v_pk_mul_f32 v[148:149], v[136:137], v[136:137]
	v_add_f32_e32 v0, v150, v0
	v_add_f32_e32 v0, v151, v0
	v_add_f32_e32 v0, v148, v0
	v_add_f32_e32 v0, v149, v0
	v_pk_mul_f32 v[150:151], v[130:131], v[130:131]
	v_pk_mul_f32 v[148:149], v[132:133], v[132:133]
	v_add_f32_e32 v0, v150, v0
	v_add_f32_e32 v0, v151, v0
	v_add_f32_e32 v0, v148, v0
	v_add_f32_e32 v0, v149, v0
	s_mov_b32 s22, 0x800000
	v_mov_b32_e32 v147, v0
	s_nop 1
	v_permlane16_swap_b32_e32 v0, v147
	s_waitcnt vmcnt(6)
	s_waitcnt lgkmcnt(0)
	v_add_f32_e32 v0, v0, v147
	v_mov_b32_e32 v147, v0
	s_nop 1
	v_permlane32_swap_b32_e32 v0, v147
	s_waitcnt lgkmcnt(0)
	v_add_f32_e32 v0, v0, v147
	v_fmamk_f32 v0, v0, 0x3c800000, v210
	v_mul_f32_e32 v147, 0x4b800000, v0
	v_cmp_gt_f32_e32 vcc, s22, v0
	s_nop 1
	v_cndmask_b32_e32 v0, v0, v147, vcc
	v_rsq_f32_e32 v0, v0
	s_nop 0
	v_mul_f32_e32 v147, 0x45800000, v0
	v_cndmask_b32_e32 v0, v0, v147, vcc
	v_mul_f32_e32 v0, v217, v0
	v_mul_f32_e32 v148, v142, v0
	v_mul_f32_e32 v160, v134, v0
	v_mul_f32_e32 v149, v143, v0
	v_mul_f32_e32 v161, v135, v0
	v_mul_f32_e32 v150, v144, v0
	v_mul_f32_e32 v158, v136, v0
	v_mul_f32_e32 v151, v145, v0
	v_mul_f32_e32 v159, v137, v0
	v_mul_f32_e32 v152, v138, v0
	v_mul_f32_e32 v168, v130, v0
	v_mul_f32_e32 v153, v139, v0
	v_mul_f32_e32 v169, v131, v0
	v_mul_f32_e32 v154, v140, v0
	v_mul_f32_e32 v166, v132, v0
	v_mul_f32_e32 v155, v141, v0
	v_mul_f32_e32 v167, v133, v0
	v_mul_f32_e32 v148, v148, v74
	v_mul_f32_e32 v160, v160, v78
	v_mul_f32_e32 v149, v149, v75
	v_mul_f32_e32 v161, v161, v79
	v_mul_f32_e32 v150, v150, v76
	v_mul_f32_e32 v158, v158, v80
	v_mul_f32_e32 v151, v151, v77
	v_mul_f32_e32 v159, v159, v81
	v_mul_f32_e32 v152, v152, v66
	v_mul_f32_e32 v168, v168, v70
	v_mul_f32_e32 v153, v153, v67
	v_mul_f32_e32 v169, v169, v71
	v_mul_f32_e32 v154, v154, v68
	v_mul_f32_e32 v166, v166, v72
	v_mul_f32_e32 v155, v155, v69
	v_mul_f32_e32 v167, v167, v73
	s_cmp_eq_u64 s[6:7], 0
	s_cbranch_scc1 .Lqkv_norope_2
	v_mul_f32_e32 v162, v160, v127
	v_mul_f32_e32 v163, v148, v127
	v_fma_f32 v148, v148, v126, -v162
	v_fma_f32 v160, v160, v126, v163
	v_mul_f32_e32 v162, v161, v129
	v_mul_f32_e32 v163, v149, v129
	v_fma_f32 v149, v149, v128, -v162
	v_fma_f32 v161, v161, v128, v163
	v_mul_f32_e32 v162, v158, v123
	v_mul_f32_e32 v163, v150, v123
	v_fma_f32 v150, v150, v122, -v162
	v_fma_f32 v158, v158, v122, v163
	v_mul_f32_e32 v162, v159, v125
	v_mul_f32_e32 v163, v151, v125
	v_fma_f32 v151, v151, v124, -v162
	v_fma_f32 v159, v159, v124, v163
	v_mul_f32_e32 v162, v168, v119
	v_mul_f32_e32 v163, v152, v119
	v_fma_f32 v152, v152, v118, -v162
	v_fma_f32 v168, v168, v118, v163
	v_mul_f32_e32 v162, v169, v121
	v_mul_f32_e32 v163, v153, v121
	v_fma_f32 v153, v153, v120, -v162
	v_fma_f32 v169, v169, v120, v163
	v_mul_f32_e32 v162, v166, v115
	v_mul_f32_e32 v163, v154, v115
	v_fma_f32 v154, v154, v114, -v162
	v_fma_f32 v166, v166, v114, v163
	v_mul_f32_e32 v162, v167, v117
	v_mul_f32_e32 v163, v155, v117
	v_fma_f32 v155, v155, v116, -v162
	v_fma_f32 v167, v167, v116, v163
.Lqkv_norope_2:
	v_mov_b32_e32 v240, s49
	v_add_u32_e32 v240, 0x80, v240
	v_and_b32_e32 v240, 0xfc0, v240
	v_or_b32_e32 v240, v240, v214
	v_lshlrev_b32_e32 v240, 8, v240
	v_mov_b32_e32 v241, 0
	v_lshl_add_u64 v[240:241], v[196:197], 0, v[240:241]
	global_load_dwordx4 v[126:129], v[240:241], off
	global_load_dwordx4 v[122:125], v[240:241], off offset:16
	global_load_dwordx4 v[118:121], v[240:241], off offset:32
	global_load_dwordx4 v[114:117], v[240:241], off offset:48
	v_lshlrev_b32_e32 v0, 7, v146
	v_lshl_add_u64 v[156:157], s[2:3], 0, v[0:1]
	v_mov_b32_e32 v207, v1
	v_lshl_add_u64 v[156:157], v[156:157], 0, v[206:207]
	v_cvt_pk_bf16_f32 v148, v148, v149
	v_cvt_pk_bf16_f32 v149, v150, v151
	v_cvt_pk_bf16_f32 v150, v152, v153
	v_cvt_pk_bf16_f32 v151, v154, v155
	global_store_dwordx4 v[156:157], v[148:151], off
	s_mov_b64 s[22:23], 0
	s_nop 0
	v_cvt_pk_bf16_f32 v148, v160, v161
	v_cvt_pk_bf16_f32 v149, v158, v159
	v_cvt_pk_bf16_f32 v150, v168, v169
	v_cvt_pk_bf16_f32 v151, v166, v167
	global_store_dwordx4 v[156:157], v[148:151], off offset:64

;   DI void operator()(const f32x4 (&acc)[2][2][4][2], const Unit& u, int wr, int wc, int fr, int fq) const {
;     ...
;           const int tt = u.pm * BM + ai * HALF + wr * 64 + (2 * mp + m2) * 16 + fr;
;           const float* rp = rope + (size_t)(tt & 4095) * 64 + 2 * (8 * fq);
; #pragma unroll
;           for (int n = 0; n < 2; ++n) { csr[m2][n][0] = *(const f32x4*)(rp + 8 * n); csr[m2][n][1] = *(const f32x4*)(rp + 8 * n + 4); }
;     ...
;           float ss = 0.f;
; #pragma unroll
;           for (int bj = 0; bj < 2; ++bj)
; #pragma unroll
;             for (int n = 0; n < 2; ++n)
; #pragma unroll
;               for (int e = 0; e < 4; ++e) ss += acc[ai][bj][m][n][e] * acc[ai][bj][m][n][e];
;           ss += __shfl_xor(ss, 16);
;           ss += __shfl_xor(ss, 32);
;           const float rinv = rsqrtf(ss * (1.f / 64.f) + EPSV);
;           float o1[8], o2[8];
; #pragma unroll
;           for (int n = 0; n < 2; ++n) {
;             f32x4 cs0 = (f32x4){1.f, 0.f, 1.f, 0.f}, cs1 = cs0;
;             if (ropeT) { cs0 = csr[m & 1][n][0]; cs1 = csr[m & 1][n][1]; }
; #pragma unroll
;             for (int e = 0; e < 4; ++e) {
;               float x1 = acc[ai][0][m][n][e] * (rinv * qs) * g4[0][n][e];
;               float x2 = acc[ai][1][m][n][e] * (rinv * qs) * g4[1][n][e];
;               float c = (e < 2) ? cs0[2 * e] : cs1[2 * (e - 2)], s = (e < 2) ? cs0[2 * e + 1] : cs1[2 * (e - 2) + 1];
;               o1[n * 4 + e] = x1 * c - x2 * s;
;               o2[n * 4 + e] = x2 * c + x1 * s;
;             }
;           }
;           u16* dst = base + (size_t)pos * 64 + 8 * fq;
;           *(uint4*)(dst) = make_uint4(pack_bf16(o1[0], o1[1]), pack_bf16(o1[2], o1[3]), pack_bf16(o1[4], o1[5]), pack_bf16(o1[6], o1[7]));
;           *(uint4*)(dst + 32) = make_uint4(pack_bf16(o2[0], o2[1]), pack_bf16(o2[2], o2[3]), pack_bf16(o2[4], o2[5]), pack_bf16(o2[6], o2[7]));
.LBB0_550:
	s_add_i32 s50, s50, s44
	s_and_b32 s2, s50, 0xff0
	v_or_b32_e32 v130, s2, v214
	s_ashr_i32 s2, s50, 7
	s_andn2_b32 s2, s2, 31
	s_add_i32 s2, s2, s48
	s_mul_hi_i32 s3, s2, 0x88000
	s_mul_i32 s2, s2, 0x88000
	s_add_u32 s2, s88, s2
	s_addc_u32 s3, s89, s3
	s_and_b64 vcc, exec, s[8:9]
	s_mov_b64 s[22:23], -1
	s_cbranch_vccnz .LBB0_552
	v_mul_f32_e32 v0, v111, v111
	v_fmac_f32_e32 v0, v110, v110
	v_fmac_f32_e32 v0, v112, v112
	v_fmac_f32_e32 v0, v113, v113
	v_fmac_f32_e32 v0, v106, v106
	v_fmac_f32_e32 v0, v107, v107
	v_fmac_f32_e32 v0, v108, v108
	v_fmac_f32_e32 v0, v109, v109
	v_pk_mul_f32 v[134:135], v[102:103], v[102:103]
	v_pk_mul_f32 v[132:133], v[104:105], v[104:105]
	v_add_f32_e32 v0, v134, v0
	v_add_f32_e32 v0, v135, v0
	v_add_f32_e32 v0, v132, v0
	v_add_f32_e32 v0, v133, v0
	v_pk_mul_f32 v[134:135], v[90:91], v[90:91]
	v_pk_mul_f32 v[132:133], v[92:93], v[92:93]
	v_add_f32_e32 v0, v134, v0
	v_add_f32_e32 v0, v135, v0
	v_add_f32_e32 v0, v132, v0
	v_add_f32_e32 v0, v133, v0
	s_mov_b32 s22, 0x800000
	v_mov_b32_e32 v131, v0
	s_nop 1
	v_permlane16_swap_b32_e32 v0, v131
	s_waitcnt vmcnt(6)
	s_waitcnt lgkmcnt(0)
	v_add_f32_e32 v0, v0, v131
	v_mov_b32_e32 v131, v0
	s_nop 1
	v_permlane32_swap_b32_e32 v0, v131
	s_waitcnt lgkmcnt(0)
	v_add_f32_e32 v0, v0, v131
	v_fmamk_f32 v0, v0, 0x3c800000, v210
	v_mul_f32_e32 v131, 0x4b800000, v0
	v_cmp_gt_f32_e32 vcc, s22, v0
	s_nop 1
	v_cndmask_b32_e32 v0, v0, v131, vcc
	v_rsq_f32_e32 v0, v0
	s_nop 0
	v_mul_f32_e32 v131, 0x45800000, v0
	v_cndmask_b32_e32 v0, v0, v131, vcc
	v_mul_f32_e32 v0, v217, v0
	v_mul_f32_e32 v132, v110, v0
	v_mul_f32_e32 v144, v102, v0
	v_mul_f32_e32 v133, v111, v0
	v_mul_f32_e32 v145, v103, v0
	v_mul_f32_e32 v134, v112, v0
	v_mul_f32_e32 v142, v104, v0
	v_mul_f32_e32 v135, v113, v0
	v_mul_f32_e32 v143, v105, v0
	v_mul_f32_e32 v136, v106, v0
	v_mul_f32_e32 v152, v90, v0
	v_mul_f32_e32 v137, v107, v0
	v_mul_f32_e32 v153, v91, v0
	v_mul_f32_e32 v138, v108, v0
	v_mul_f32_e32 v150, v92, v0
	v_mul_f32_e32 v139, v109, v0
	v_mul_f32_e32 v151, v93, v0
	v_mul_f32_e32 v132, v132, v74
	v_mul_f32_e32 v144, v144, v78
	v_mul_f32_e32 v133, v133, v75
	v_mul_f32_e32 v145, v145, v79
	v_mul_f32_e32 v134, v134, v76
	v_mul_f32_e32 v142, v142, v80
	v_mul_f32_e32 v135, v135, v77
	v_mul_f32_e32 v143, v143, v81
	v_mul_f32_e32 v136, v136, v66
	v_mul_f32_e32 v152, v152, v70
	v_mul_f32_e32 v137, v137, v67
	v_mul_f32_e32 v153, v153, v71
	v_mul_f32_e32 v138, v138, v68
	v_mul_f32_e32 v150, v150, v72
	v_mul_f32_e32 v139, v139, v69
	v_mul_f32_e32 v151, v151, v73
	s_cmp_eq_u64 s[6:7], 0
	s_cbranch_scc1 .Lqkv_norope_3
	v_mul_f32_e32 v146, v144, v95
	v_mul_f32_e32 v147, v132, v95
	v_fma_f32 v132, v132, v94, -v146
	v_fma_f32 v144, v144, v94, v147
	v_mul_f32_e32 v146, v145, v97
	v_mul_f32_e32 v147, v133, v97
	v_fma_f32 v133, v133, v96, -v146
	v_fma_f32 v145, v145, v96, v147
	v_mul_f32_e32 v146, v142, v99
	v_mul_f32_e32 v147, v134, v99
	v_fma_f32 v134, v134, v98, -v146
	v_fma_f32 v142, v142, v98, v147
	v_mul_f32_e32 v146, v143, v101
	v_mul_f32_e32 v147, v135, v101
	v_fma_f32 v135, v135, v100, -v146
	v_fma_f32 v143, v143, v100, v147
	v_mul_f32_e32 v146, v152, v87
	v_mul_f32_e32 v147, v136, v87
	v_fma_f32 v136, v136, v86, -v146
	v_fma_f32 v152, v152, v86, v147
	v_mul_f32_e32 v146, v153, v89
	v_mul_f32_e32 v147, v137, v89
	v_fma_f32 v137, v137, v88, -v146
	v_fma_f32 v153, v153, v88, v147
	v_mul_f32_e32 v146, v150, v83
	v_mul_f32_e32 v147, v138, v83
	v_fma_f32 v138, v138, v82, -v146
	v_fma_f32 v150, v150, v82, v147
	v_mul_f32_e32 v146, v151, v85
	v_mul_f32_e32 v147, v139, v85
	v_fma_f32 v139, v139, v84, -v146
	v_fma_f32 v151, v151, v84, v147
.Lqkv_norope_3:
	v_mov_b32_e32 v240, s49
	v_add_u32_e32 v240, 0x80, v240
	v_and_b32_e32 v240, 0xfc0, v240
	v_or_b32_e32 v240, v240, v214
	v_add_u32_e32 v240, 0x10, v240
	v_lshlrev_b32_e32 v240, 8, v240
	v_mov_b32_e32 v241, 0
	v_lshl_add_u64 v[240:241], v[196:197], 0, v[240:241]
	global_load_dwordx4 v[94:97], v[240:241], off
	global_load_dwordx4 v[98:101], v[240:241], off offset:16
	global_load_dwordx4 v[86:89], v[240:241], off offset:32
	global_load_dwordx4 v[82:85], v[240:241], off offset:48
	v_lshlrev_b32_e32 v0, 7, v130
	v_lshl_add_u64 v[140:141], s[2:3], 0, v[0:1]
	v_mov_b32_e32 v207, v1
	v_lshl_add_u64 v[140:141], v[140:141], 0, v[206:207]
	v_cvt_pk_bf16_f32 v132, v132, v133
	v_cvt_pk_bf16_f32 v133, v134, v135
	v_cvt_pk_bf16_f32 v134, v136, v137
	v_cvt_pk_bf16_f32 v135, v138, v139
	global_store_dwordx4 v[140:141], v[132:135], off
	s_mov_b64 s[22:23], 0
	s_nop 0
	v_cvt_pk_bf16_f32 v132, v144, v145
	v_cvt_pk_bf16_f32 v133, v142, v143
	v_cvt_pk_bf16_f32 v134, v152, v153
	v_cvt_pk_bf16_f32 v135, v150, v151
	global_store_dwordx4 v[140:141], v[132:135], off offset:64

;   DI void operator()(const f32x4 (&acc)[2][2][4][2], const Unit& u, int wr, int wc, int fr, int fq) const {
;     ...
;           const int tt = u.pm * BM + ai * HALF + wr * 64 + (2 * mp + m2) * 16 + fr;
;           const float* rp = rope + (size_t)(tt & 4095) * 64 + 2 * (8 * fq);
; #pragma unroll
;           for (int n = 0; n < 2; ++n) { csr[m2][n][0] = *(const f32x4*)(rp + 8 * n); csr[m2][n][1] = *(const f32x4*)(rp + 8 * n + 4); }
;     ...
;           float ss = 0.f;
; #pragma unroll
;           for (int bj = 0; bj < 2; ++bj)
; #pragma unroll
;             for (int n = 0; n < 2; ++n)
; #pragma unroll
;               for (int e = 0; e < 4; ++e) ss += acc[ai][bj][m][n][e] * acc[ai][bj][m][n][e];
;           ss += __shfl_xor(ss, 16);
;           ss += __shfl_xor(ss, 32);
;           const float rinv = rsqrtf(ss * (1.f / 64.f) + EPSV);
;           float o1[8], o2[8];
; #pragma unroll
;           for (int n = 0; n < 2; ++n) {
;             f32x4 cs0 = (f32x4){1.f, 0.f, 1.f, 0.f}, cs1 = cs0;
;             if (ropeT) { cs0 = csr[m & 1][n][0]; cs1 = csr[m & 1][n][1]; }
; #pragma unroll
;             for (int e = 0; e < 4; ++e) {
;               float x1 = acc[ai][0][m][n][e] * (rinv * qs) * g4[0][n][e];
;               float x2 = acc[ai][1][m][n][e] * (rinv * qs) * g4[1][n][e];
;               float c = (e < 2) ? cs0[2 * e] : cs1[2 * (e - 2)], s = (e < 2) ? cs0[2 * e + 1] : cs1[2 * (e - 2) + 1];
;               o1[n * 4 + e] = x1 * c - x2 * s;
;               o2[n * 4 + e] = x2 * c + x1 * s;
;             }
;           }
;           u16* dst = base + (size_t)pos * 64 + 8 * fq;
;           *(uint4*)(dst) = make_uint4(pack_bf16(o1[0], o1[1]), pack_bf16(o1[2], o1[3]), pack_bf16(o1[4], o1[5]), pack_bf16(o1[6], o1[7]));
;           *(uint4*)(dst + 32) = make_uint4(pack_bf16(o2[0], o2[1]), pack_bf16(o2[2], o2[3]), pack_bf16(o2[4], o2[5]), pack_bf16(o2[6], o2[7]));
.LBB0_556:
	s_ashr_i32 s2, s2, 7
	s_andn2_b32 s2, s2, 31
	s_add_i32 s2, s2, s48
	s_mul_hi_i32 s3, s2, 0x88000
	s_mul_i32 s2, s2, 0x88000
	s_add_u32 s2, s88, s2
	s_addc_u32 s3, s89, s3
	s_and_b64 vcc, exec, s[8:9]
	s_mov_b64 s[22:23], -1
	s_cbranch_vccnz .LBB0_558
	v_mul_f32_e32 v91, v63, v63
	v_fmac_f32_e32 v91, v62, v62
	v_fmac_f32_e32 v91, v64, v64
	v_fmac_f32_e32 v91, v65, v65
	v_fmac_f32_e32 v91, v58, v58
	v_fmac_f32_e32 v91, v59, v59
	v_fmac_f32_e32 v91, v60, v60
	v_fmac_f32_e32 v91, v61, v61
	v_pk_mul_f32 v[102:103], v[54:55], v[54:55]
	v_pk_mul_f32 v[92:93], v[56:57], v[56:57]
	v_add_f32_e32 v91, v102, v91
	v_add_f32_e32 v91, v103, v91
	v_add_f32_e32 v91, v92, v91
	v_add_f32_e32 v91, v93, v91
	v_pk_mul_f32 v[102:103], v[50:51], v[50:51]
	v_pk_mul_f32 v[92:93], v[52:53], v[52:53]
	v_add_f32_e32 v91, v102, v91
	v_add_f32_e32 v91, v103, v91
	v_add_f32_e32 v91, v92, v91
	v_add_f32_e32 v91, v93, v91
	s_mov_b32 s22, 0x800000
	v_mov_b32_e32 v92, v91
	s_nop 1
	v_permlane16_swap_b32_e32 v91, v92
	s_waitcnt vmcnt(6)
	s_waitcnt lgkmcnt(0)
	v_add_f32_e32 v91, v91, v92
	v_mov_b32_e32 v92, v91
	s_nop 1
	v_permlane32_swap_b32_e32 v91, v92
	s_waitcnt lgkmcnt(0)
	v_add_f32_e32 v91, v91, v92
	v_fmamk_f32 v91, v91, 0x3c800000, v210
	v_mul_f32_e32 v92, 0x4b800000, v91
	v_cmp_gt_f32_e32 vcc, s22, v91
	s_nop 1
	v_cndmask_b32_e32 v91, v91, v92, vcc
	v_rsq_f32_e32 v91, v91
	s_nop 0
	v_mul_f32_e32 v92, 0x45800000, v91
	v_cndmask_b32_e32 v91, v91, v92, vcc
	v_mul_f32_e32 v92, v217, v91
	v_mul_f32_e32 v102, v62, v92
	v_mul_f32_e32 v130, v54, v92
	v_mul_f32_e32 v103, v63, v92
	v_mul_f32_e32 v131, v55, v92
	v_mul_f32_e32 v104, v64, v92
	v_mul_f32_e32 v112, v56, v92
	v_mul_f32_e32 v105, v65, v92
	v_mul_f32_e32 v113, v57, v92
	v_mul_f32_e32 v106, v58, v92
	v_mul_f32_e32 v138, v50, v92
	v_mul_f32_e32 v107, v59, v92
	v_mul_f32_e32 v139, v51, v92
	v_mul_f32_e32 v134, v52, v92
	v_mul_f32_e32 v93, v61, v92
	v_mul_f32_e32 v135, v53, v92
	v_mul_f32_e32 v92, v60, v92
	v_mul_f32_e32 v102, v102, v74
	v_mul_f32_e32 v130, v130, v78
	v_mul_f32_e32 v103, v103, v75
	v_mul_f32_e32 v131, v131, v79
	v_mul_f32_e32 v104, v104, v76
	v_mul_f32_e32 v112, v112, v80
	v_mul_f32_e32 v105, v105, v77
	v_mul_f32_e32 v113, v113, v81
	v_mul_f32_e32 v106, v106, v66
	v_mul_f32_e32 v138, v138, v70
	v_mul_f32_e32 v107, v107, v67
	v_mul_f32_e32 v139, v139, v71
	v_mul_f32_e32 v134, v134, v72
	v_mul_f32_e32 v93, v93, v69
	v_mul_f32_e32 v135, v135, v73
	v_mul_f32_e32 v92, v92, v68
	s_cmp_eq_u64 s[6:7], 0
	s_cbranch_scc1 .Lqkv_norope_4
	v_mul_f32_e32 v110, v130, v127
	v_mul_f32_e32 v111, v102, v127
	v_fma_f32 v102, v102, v126, -v110
	v_fma_f32 v130, v130, v126, v111
	v_mul_f32_e32 v110, v131, v129
	v_mul_f32_e32 v111, v103, v129
	v_fma_f32 v103, v103, v128, -v110
	v_fma_f32 v131, v131, v128, v111
	v_mul_f32_e32 v110, v112, v123
	v_mul_f32_e32 v111, v104, v123
	v_fma_f32 v104, v104, v122, -v110
	v_fma_f32 v112, v112, v122, v111
	v_mul_f32_e32 v110, v113, v125
	v_mul_f32_e32 v111, v105, v125
	v_fma_f32 v105, v105, v124, -v110
	v_fma_f32 v113, v113, v124, v111
	v_mul_f32_e32 v110, v138, v119
	v_mul_f32_e32 v111, v106, v119
	v_fma_f32 v106, v106, v118, -v110
	v_fma_f32 v138, v138, v118, v111
	v_mul_f32_e32 v110, v139, v121
	v_mul_f32_e32 v111, v107, v121
	v_fma_f32 v107, v107, v120, -v110
	v_fma_f32 v139, v139, v120, v111
	v_mul_f32_e32 v110, v134, v115
	v_mul_f32_e32 v111, v92, v115
	v_fma_f32 v92, v92, v114, -v110
	v_fma_f32 v134, v134, v114, v111
	v_mul_f32_e32 v110, v135, v117
	v_mul_f32_e32 v111, v93, v117
	v_fma_f32 v93, v93, v116, -v110
	v_fma_f32 v135, v135, v116, v111
.Lqkv_norope_4:
	v_mov_b32_e32 v240, s49
	v_add_u32_e32 v240, 0x80, v240
	v_and_b32_e32 v240, 0xfc0, v240
	v_or_b32_e32 v240, v240, v214
	v_add_u32_e32 v240, 0x20, v240
	v_lshlrev_b32_e32 v240, 8, v240
	v_mov_b32_e32 v241, 0
	v_lshl_add_u64 v[240:241], v[196:197], 0, v[240:241]
	global_load_dwordx4 v[126:129], v[240:241], off
	global_load_dwordx4 v[122:125], v[240:241], off offset:16
	global_load_dwordx4 v[118:121], v[240:241], off offset:32
	global_load_dwordx4 v[114:117], v[240:241], off offset:48
	v_lshlrev_b32_e32 v108, 7, v90
	v_mov_b32_e32 v109, v1
	v_lshl_add_u64 v[108:109], s[2:3], 0, v[108:109]
	v_mov_b32_e32 v207, v1
	v_lshl_add_u64 v[108:109], v[108:109], 0, v[206:207]
	v_cvt_pk_bf16_f32 v102, v102, v103
	v_cvt_pk_bf16_f32 v103, v104, v105
	v_cvt_pk_bf16_f32 v104, v106, v107
	v_cvt_pk_bf16_f32 v105, v92, v93
	global_store_dwordx4 v[108:109], v[102:105], off
	s_mov_b64 s[22:23], 0
	s_nop 0
	v_cvt_pk_bf16_f32 v102, v130, v131
	v_cvt_pk_bf16_f32 v103, v112, v113
	v_cvt_pk_bf16_f32 v104, v138, v139
	v_cvt_pk_bf16_f32 v105, v134, v135
	global_store_dwordx4 v[108:109], v[102:105], off offset:64

;   DI void operator()(const f32x4 (&acc)[2][2][4][2], const Unit& u, int wr, int wc, int fr, int fq) const {
;     ...
;           const int tt = u.pm * BM + ai * HALF + wr * 64 + (2 * mp + m2) * 16 + fr;
;           const float* rp = rope + (size_t)(tt & 4095) * 64 + 2 * (8 * fq);
; #pragma unroll
;           for (int n = 0; n < 2; ++n) { csr[m2][n][0] = *(const f32x4*)(rp + 8 * n); csr[m2][n][1] = *(const f32x4*)(rp + 8 * n + 4); }
;     ...
;           float ss = 0.f;
; #pragma unroll
;           for (int bj = 0; bj < 2; ++bj)
; #pragma unroll
;             for (int n = 0; n < 2; ++n)
; #pragma unroll
;               for (int e = 0; e < 4; ++e) ss += acc[ai][bj][m][n][e] * acc[ai][bj][m][n][e];
;           ss += __shfl_xor(ss, 16);
;           ss += __shfl_xor(ss, 32);
;           const float rinv = rsqrtf(ss * (1.f / 64.f) + EPSV);
;           float o1[8], o2[8];
; #pragma unroll
;           for (int n = 0; n < 2; ++n) {
;             f32x4 cs0 = (f32x4){1.f, 0.f, 1.f, 0.f}, cs1 = cs0;
;             if (ropeT) { cs0 = csr[m & 1][n][0]; cs1 = csr[m & 1][n][1]; }
; #pragma unroll
;             for (int e = 0; e < 4; ++e) {
;               float x1 = acc[ai][0][m][n][e] * (rinv * qs) * g4[0][n][e];
;               float x2 = acc[ai][1][m][n][e] * (rinv * qs) * g4[1][n][e];
;               float c = (e < 2) ? cs0[2 * e] : cs1[2 * (e - 2)], s = (e < 2) ? cs0[2 * e + 1] : cs1[2 * (e - 2) + 1];
;               o1[n * 4 + e] = x1 * c - x2 * s;
;               o2[n * 4 + e] = x2 * c + x1 * s;
;             }
;           }
;           u16* dst = base + (size_t)pos * 64 + 8 * fq;
;           *(uint4*)(dst) = make_uint4(pack_bf16(o1[0], o1[1]), pack_bf16(o1[2], o1[3]), pack_bf16(o1[4], o1[5]), pack_bf16(o1[6], o1[7]));
;           *(uint4*)(dst + 32) = make_uint4(pack_bf16(o2[0], o2[1]), pack_bf16(o2[2], o2[3]), pack_bf16(o2[4], o2[5]), pack_bf16(o2[6], o2[7]));
.LBB0_560:
	s_add_i32 s2, s49, 0x90
	s_and_b32 s3, s2, 0xfd0
	s_ashr_i32 s2, s2, 7
	s_andn2_b32 s2, s2, 31
	s_add_i32 s2, s2, s48
	v_or_b32_e32 v50, s3, v214
	s_mul_hi_i32 s3, s2, 0x88000
	s_mul_i32 s2, s2, 0x88000
	s_add_u32 s2, s88, s2
	s_addc_u32 s3, s89, s3
	s_and_b64 vcc, exec, s[8:9]
	s_mov_b64 s[22:23], -1
	s_cbranch_vccnz .LBB0_572
	v_mul_f32_e32 v51, v47, v47
	v_fmac_f32_e32 v51, v46, v46
	v_fmac_f32_e32 v51, v48, v48
	v_fmac_f32_e32 v51, v49, v49
	v_fmac_f32_e32 v51, v42, v42
	v_fmac_f32_e32 v51, v43, v43
	v_fmac_f32_e32 v51, v44, v44
	v_fmac_f32_e32 v51, v45, v45
	v_pk_mul_f32 v[54:55], v[38:39], v[38:39]
	v_pk_mul_f32 v[52:53], v[40:41], v[40:41]
	v_add_f32_e32 v51, v54, v51
	v_add_f32_e32 v51, v55, v51
	v_add_f32_e32 v51, v52, v51
	v_add_f32_e32 v51, v53, v51
	v_pk_mul_f32 v[54:55], v[34:35], v[34:35]
	v_pk_mul_f32 v[52:53], v[36:37], v[36:37]
	v_add_f32_e32 v51, v54, v51
	v_add_f32_e32 v51, v55, v51
	v_add_f32_e32 v51, v52, v51
	v_add_f32_e32 v51, v53, v51
	s_mov_b32 s22, 0x800000
	v_mov_b32_e32 v52, v51
	s_nop 1
	v_permlane16_swap_b32_e32 v51, v52
	s_waitcnt vmcnt(6)
	s_waitcnt lgkmcnt(0)
	v_add_f32_e32 v51, v51, v52
	v_mov_b32_e32 v52, v51
	s_nop 1
	v_permlane32_swap_b32_e32 v51, v52
	s_waitcnt lgkmcnt(0)
	v_add_f32_e32 v51, v51, v52
	v_fmamk_f32 v51, v51, 0x3c800000, v210
	v_mul_f32_e32 v52, 0x4b800000, v51
	v_cmp_gt_f32_e32 vcc, s22, v51
	s_nop 1
	v_cndmask_b32_e32 v51, v51, v52, vcc
	v_rsq_f32_e32 v51, v51
	s_nop 0
	v_mul_f32_e32 v52, 0x45800000, v51
	v_cndmask_b32_e32 v51, v51, v52, vcc
	v_mul_f32_e32 v52, v217, v51
	v_mul_f32_e32 v54, v46, v52
	v_mul_f32_e32 v90, v38, v52
	v_mul_f32_e32 v55, v47, v52
	v_mul_f32_e32 v91, v39, v52
	v_mul_f32_e32 v56, v48, v52
	v_mul_f32_e32 v64, v40, v52
	v_mul_f32_e32 v57, v49, v52
	v_mul_f32_e32 v65, v41, v52
	v_mul_f32_e32 v58, v42, v52
	v_mul_f32_e32 v106, v34, v52
	v_mul_f32_e32 v59, v43, v52
	v_mul_f32_e32 v107, v35, v52
	v_mul_f32_e32 v60, v44, v52
	v_mul_f32_e32 v102, v36, v52
	v_mul_f32_e32 v61, v45, v52
	v_mul_f32_e32 v103, v37, v52
	v_mul_f32_e32 v54, v54, v74
	v_mul_f32_e32 v90, v90, v78
	v_mul_f32_e32 v55, v55, v75
	v_mul_f32_e32 v91, v91, v79
	v_mul_f32_e32 v56, v56, v76
	v_mul_f32_e32 v64, v64, v80
	v_mul_f32_e32 v57, v57, v77
	v_mul_f32_e32 v65, v65, v81
	v_mul_f32_e32 v58, v58, v66
	v_mul_f32_e32 v106, v106, v70
	v_mul_f32_e32 v59, v59, v67
	v_mul_f32_e32 v107, v107, v71
	v_mul_f32_e32 v60, v60, v68
	v_mul_f32_e32 v102, v102, v72
	v_mul_f32_e32 v61, v61, v69
	v_mul_f32_e32 v103, v103, v73
	s_cmp_eq_u64 s[6:7], 0
	s_cbranch_scc1 .Lqkv_norope_5
	v_mul_f32_e32 v92, v90, v95
	v_mul_f32_e32 v93, v54, v95
	v_fma_f32 v54, v54, v94, -v92
	v_fma_f32 v90, v90, v94, v93
	v_mul_f32_e32 v92, v91, v97
	v_mul_f32_e32 v93, v55, v97
	v_fma_f32 v55, v55, v96, -v92
	v_fma_f32 v91, v91, v96, v93
	v_mul_f32_e32 v92, v64, v99
	v_mul_f32_e32 v93, v56, v99
	v_fma_f32 v56, v56, v98, -v92
	v_fma_f32 v64, v64, v98, v93
	v_mul_f32_e32 v92, v65, v101
	v_mul_f32_e32 v93, v57, v101
	v_fma_f32 v57, v57, v100, -v92
	v_fma_f32 v65, v65, v100, v93
	v_mul_f32_e32 v92, v106, v87
	v_mul_f32_e32 v93, v58, v87
	v_fma_f32 v58, v58, v86, -v92
	v_fma_f32 v106, v106, v86, v93
	v_mul_f32_e32 v92, v107, v89
	v_mul_f32_e32 v93, v59, v89
	v_fma_f32 v59, v59, v88, -v92
	v_fma_f32 v107, v107, v88, v93
	v_mul_f32_e32 v92, v102, v83
	v_mul_f32_e32 v93, v60, v83
	v_fma_f32 v60, v60, v82, -v92
	v_fma_f32 v102, v102, v82, v93
	v_mul_f32_e32 v92, v103, v85
	v_mul_f32_e32 v93, v61, v85
	v_fma_f32 v61, v61, v84, -v92
	v_fma_f32 v103, v103, v84, v93
.Lqkv_norope_5:
	v_mov_b32_e32 v240, s49
	v_add_u32_e32 v240, 0x80, v240
	v_and_b32_e32 v240, 0xfc0, v240
	v_or_b32_e32 v240, v240, v214
	v_add_u32_e32 v240, 0x30, v240
	v_lshlrev_b32_e32 v240, 8, v240
	v_mov_b32_e32 v241, 0
	v_lshl_add_u64 v[240:241], v[196:197], 0, v[240:241]
	global_load_dwordx4 v[94:97], v[240:241], off
	global_load_dwordx4 v[98:101], v[240:241], off offset:16
	global_load_dwordx4 v[86:89], v[240:241], off offset:32
	global_load_dwordx4 v[82:85], v[240:241], off offset:48
	v_mov_b32_e32 v207, v1
	v_lshlrev_b32_e32 v52, 7, v50
	v_mov_b32_e32 v53, v1
	v_lshl_add_u64 v[52:53], s[2:3], 0, v[52:53]
	v_lshl_add_u64 v[62:63], v[52:53], 0, v[206:207]
	v_cvt_pk_bf16_f32 v52, v54, v55
	v_cvt_pk_bf16_f32 v53, v56, v57
	v_cvt_pk_bf16_f32 v54, v58, v59
	v_cvt_pk_bf16_f32 v55, v60, v61
	global_store_dwordx4 v[62:63], v[52:55], off
	s_nop 1
	v_cvt_pk_bf16_f32 v52, v90, v91
	v_cvt_pk_bf16_f32 v53, v64, v65
	v_cvt_pk_bf16_f32 v54, v106, v107
	v_cvt_pk_bf16_f32 v55, v102, v103
	global_store_dwordx4 v[62:63], v[52:55], off offset:64
	s_cbranch_execz .LBB0_573

;   DI void operator()(const f32x4 (&acc)[2][2][4][2], const Unit& u, int wr, int wc, int fr, int fq) const {
;     ...
;           const int tt = u.pm * BM + ai * HALF + wr * 64 + (2 * mp + m2) * 16 + fr;
;           const float* rp = rope + (size_t)(tt & 4095) * 64 + 2 * (8 * fq);
; #pragma unroll
;           for (int n = 0; n < 2; ++n) { csr[m2][n][0] = *(const f32x4*)(rp + 8 * n); csr[m2][n][1] = *(const f32x4*)(rp + 8 * n + 4); }
;     ...
;           float ss = 0.f;
; #pragma unroll
;           for (int bj = 0; bj < 2; ++bj)
; #pragma unroll
;             for (int n = 0; n < 2; ++n)
; #pragma unroll
;               for (int e = 0; e < 4; ++e) ss += acc[ai][bj][m][n][e] * acc[ai][bj][m][n][e];
;           ss += __shfl_xor(ss, 16);
;           ss += __shfl_xor(ss, 32);
;           const float rinv = rsqrtf(ss * (1.f / 64.f) + EPSV);
;           float o1[8], o2[8];
; #pragma unroll
;           for (int n = 0; n < 2; ++n) {
;             f32x4 cs0 = (f32x4){1.f, 0.f, 1.f, 0.f}, cs1 = cs0;
;             if (ropeT) { cs0 = csr[m & 1][n][0]; cs1 = csr[m & 1][n][1]; }
; #pragma unroll
;             for (int e = 0; e < 4; ++e) {
;               float x1 = acc[ai][0][m][n][e] * (rinv * qs) * g4[0][n][e];
;               float x2 = acc[ai][1][m][n][e] * (rinv * qs) * g4[1][n][e];
;               float c = (e < 2) ? cs0[2 * e] : cs1[2 * (e - 2)], s = (e < 2) ? cs0[2 * e + 1] : cs1[2 * (e - 2) + 1];
;               o1[n * 4 + e] = x1 * c - x2 * s;
;               o2[n * 4 + e] = x2 * c + x1 * s;
;             }
;           }
.LBB0_563:
.LBB0_564:
	s_add_i32 s2, s49, 0xa0
	s_and_b32 s3, s2, 0xfe0
	s_ashr_i32 s2, s2, 7
	s_andn2_b32 s2, s2, 31
	s_add_i32 s2, s2, s48
	v_or_b32_e32 v34, s3, v214
	s_mul_hi_i32 s3, s2, 0x88000
	s_mul_i32 s2, s2, 0x88000
	s_add_u32 s2, s88, s2
	s_addc_u32 s3, s89, s3
	s_and_b64 vcc, exec, s[8:9]
	s_mov_b64 s[10:11], -1
	s_cbranch_vccnz .LBB0_566
	v_mul_f32_e32 v0, v31, v31
	v_fmac_f32_e32 v0, v30, v30
	v_fmac_f32_e32 v0, v32, v32
	v_fmac_f32_e32 v0, v33, v33
	v_fmac_f32_e32 v0, v26, v26
	v_fmac_f32_e32 v0, v27, v27
	v_fmac_f32_e32 v0, v28, v28
	v_fmac_f32_e32 v0, v29, v29
	v_pk_mul_f32 v[38:39], v[22:23], v[22:23]
	v_pk_mul_f32 v[36:37], v[24:25], v[24:25]
	v_add_f32_e32 v0, v38, v0
	v_add_f32_e32 v0, v39, v0
	v_add_f32_e32 v0, v36, v0
	v_add_f32_e32 v0, v37, v0
	v_pk_mul_f32 v[38:39], v[18:19], v[18:19]
	v_pk_mul_f32 v[36:37], v[20:21], v[20:21]
	v_add_f32_e32 v0, v38, v0
	v_add_f32_e32 v0, v39, v0
	v_add_f32_e32 v0, v36, v0
	v_add_f32_e32 v0, v37, v0
	s_mov_b32 s10, 0x800000
	v_mov_b32_e32 v35, v0
	s_nop 1
	v_permlane16_swap_b32_e32 v0, v35
	s_waitcnt vmcnt(6)
	s_waitcnt lgkmcnt(0)
	v_add_f32_e32 v0, v0, v35
	v_mov_b32_e32 v35, v0
	s_nop 1
	v_permlane32_swap_b32_e32 v0, v35
	s_waitcnt lgkmcnt(0)
	v_add_f32_e32 v0, v0, v35
	v_fmamk_f32 v0, v0, 0x3c800000, v210
	v_mul_f32_e32 v35, 0x4b800000, v0
	v_cmp_gt_f32_e32 vcc, s10, v0
	s_nop 1
	v_cndmask_b32_e32 v0, v0, v35, vcc
	v_rsq_f32_e32 v0, v0
	s_nop 0
	v_mul_f32_e32 v35, 0x45800000, v0
	v_cndmask_b32_e32 v0, v0, v35, vcc
	v_mul_f32_e32 v0, v217, v0
	v_mul_f32_e32 v36, v30, v0
	v_mul_f32_e32 v48, v22, v0
	v_mul_f32_e32 v37, v31, v0
	v_mul_f32_e32 v49, v23, v0
	v_mul_f32_e32 v38, v32, v0
	v_mul_f32_e32 v46, v24, v0
	v_mul_f32_e32 v39, v33, v0
	v_mul_f32_e32 v47, v25, v0
	v_mul_f32_e32 v40, v26, v0
	v_mul_f32_e32 v56, v18, v0
	v_mul_f32_e32 v41, v27, v0
	v_mul_f32_e32 v57, v19, v0
	v_mul_f32_e32 v42, v28, v0
	v_mul_f32_e32 v54, v20, v0
	v_mul_f32_e32 v43, v29, v0
	v_mul_f32_e32 v55, v21, v0
	v_mul_f32_e32 v36, v36, v74
	v_mul_f32_e32 v48, v48, v78
	v_mul_f32_e32 v37, v37, v75
	v_mul_f32_e32 v49, v49, v79
	v_mul_f32_e32 v38, v38, v76
	v_mul_f32_e32 v46, v46, v80
	v_mul_f32_e32 v39, v39, v77
	v_mul_f32_e32 v47, v47, v81
	v_mul_f32_e32 v40, v40, v66
	v_mul_f32_e32 v56, v56, v70
	v_mul_f32_e32 v41, v41, v67
	v_mul_f32_e32 v57, v57, v71
	v_mul_f32_e32 v42, v42, v68
	v_mul_f32_e32 v54, v54, v72
	v_mul_f32_e32 v43, v43, v69
	v_mul_f32_e32 v55, v55, v73
	s_cmp_eq_u64 s[6:7], 0
	s_cbranch_scc1 .Lqkv_norope_6
	v_mul_f32_e32 v50, v48, v127
	v_mul_f32_e32 v51, v36, v127
	v_fma_f32 v36, v36, v126, -v50
	v_fma_f32 v48, v48, v126, v51
	v_mul_f32_e32 v50, v49, v129
	v_mul_f32_e32 v51, v37, v129
	v_fma_f32 v37, v37, v128, -v50
	v_fma_f32 v49, v49, v128, v51
	v_mul_f32_e32 v50, v46, v123
	v_mul_f32_e32 v51, v38, v123
	v_fma_f32 v38, v38, v122, -v50
	v_fma_f32 v46, v46, v122, v51
	v_mul_f32_e32 v50, v47, v125
	v_mul_f32_e32 v51, v39, v125
	v_fma_f32 v39, v39, v124, -v50
	v_fma_f32 v47, v47, v124, v51
	v_mul_f32_e32 v50, v56, v119
	v_mul_f32_e32 v51, v40, v119
	v_fma_f32 v40, v40, v118, -v50
	v_fma_f32 v56, v56, v118, v51
	v_mul_f32_e32 v50, v57, v121
	v_mul_f32_e32 v51, v41, v121
	v_fma_f32 v41, v41, v120, -v50
	v_fma_f32 v57, v57, v120, v51
	v_mul_f32_e32 v50, v54, v115
	v_mul_f32_e32 v51, v42, v115
	v_fma_f32 v42, v42, v114, -v50
	v_fma_f32 v54, v54, v114, v51
	v_mul_f32_e32 v50, v55, v117
	v_mul_f32_e32 v51, v43, v117
	v_fma_f32 v43, v43, v116, -v50
	v_fma_f32 v55, v55, v116, v51

;   DI void operator()(const f32x4 (&acc)[2][2][4][2], const Unit& u, int wr, int wc, int fr, int fq) const {
;     ...
;           float ss = 0.f;
; #pragma unroll
;           for (int bj = 0; bj < 2; ++bj)
; #pragma unroll
;             for (int n = 0; n < 2; ++n)
; #pragma unroll
;               for (int e = 0; e < 4; ++e) ss += acc[ai][bj][m][n][e] * acc[ai][bj][m][n][e];
;           ss += __shfl_xor(ss, 16);
;           ss += __shfl_xor(ss, 32);
;           const float rinv = rsqrtf(ss * (1.f / 64.f) + EPSV);
;           float o1[8], o2[8];
; #pragma unroll
;           for (int n = 0; n < 2; ++n) {
;             f32x4 cs0 = (f32x4){1.f, 0.f, 1.f, 0.f}, cs1 = cs0;
;             if (ropeT) { cs0 = csr[m & 1][n][0]; cs1 = csr[m & 1][n][1]; }
; #pragma unroll
;             for (int e = 0; e < 4; ++e) {
;               float x1 = acc[ai][0][m][n][e] * (rinv * qs) * g4[0][n][e];
;               float x2 = acc[ai][1][m][n][e] * (rinv * qs) * g4[1][n][e];
;               float c = (e < 2) ? cs0[2 * e] : cs1[2 * (e - 2)], s = (e < 2) ? cs0[2 * e + 1] : cs1[2 * (e - 2) + 1];
;               o1[n * 4 + e] = x1 * c - x2 * s;
;               o2[n * 4 + e] = x2 * c + x1 * s;
;             }
;           }
.LBB0_568:
	s_addk_i32 s49, 0xb0
	s_and_b32 s2, s49, 0xff0
	v_or_b32_e32 v18, s2, v214
	s_ashr_i32 s2, s49, 7
	s_andn2_b32 s2, s2, 31
	s_add_i32 s2, s2, s48
	s_mul_hi_i32 s3, s2, 0x88000
	s_mul_i32 s2, s2, 0x88000
	s_add_u32 s2, s88, s2
	s_addc_u32 s3, s89, s3
	s_and_b64 vcc, exec, s[8:9]
	s_mov_b64 s[8:9], -1
	s_cbranch_vccnz .LBB0_570
	v_mul_f32_e32 v0, v15, v15
	v_fmac_f32_e32 v0, v14, v14
	v_fmac_f32_e32 v0, v16, v16
	v_fmac_f32_e32 v0, v17, v17
	v_fmac_f32_e32 v0, v10, v10
	v_fmac_f32_e32 v0, v11, v11
	v_fmac_f32_e32 v0, v12, v12
	v_fmac_f32_e32 v0, v13, v13
	v_pk_mul_f32 v[22:23], v[6:7], v[6:7]
	v_pk_mul_f32 v[20:21], v[8:9], v[8:9]
	v_add_f32_e32 v0, v22, v0
	v_add_f32_e32 v0, v23, v0
	v_add_f32_e32 v0, v20, v0
	v_add_f32_e32 v0, v21, v0
	v_pk_mul_f32 v[22:23], v[2:3], v[2:3]
	v_pk_mul_f32 v[20:21], v[4:5], v[4:5]
	v_add_f32_e32 v0, v22, v0
	v_add_f32_e32 v0, v23, v0
	v_add_f32_e32 v0, v20, v0
	v_add_f32_e32 v0, v21, v0
	s_mov_b32 s8, 0x800000
	v_mov_b32_e32 v19, v0
	s_nop 1
	v_permlane16_swap_b32_e32 v0, v19
	s_waitcnt vmcnt(2)
	s_waitcnt lgkmcnt(0)
	v_add_f32_e32 v0, v0, v19
	v_mov_b32_e32 v19, v0
	s_nop 1
	v_permlane32_swap_b32_e32 v0, v19
	s_waitcnt lgkmcnt(0)
	v_add_f32_e32 v0, v0, v19
	v_fmamk_f32 v0, v0, 0x3c800000, v210
	v_mul_f32_e32 v19, 0x4b800000, v0
	v_cmp_gt_f32_e32 vcc, s8, v0
	s_nop 1
	v_cndmask_b32_e32 v0, v0, v19, vcc
	v_rsq_f32_e32 v0, v0
	s_nop 0
	v_mul_f32_e32 v19, 0x45800000, v0
	v_cndmask_b32_e32 v0, v0, v19, vcc
	v_mul_f32_e32 v0, v217, v0
	v_mul_f32_e32 v20, v14, v0
	v_mul_f32_e32 v32, v6, v0
	v_mul_f32_e32 v21, v15, v0
	v_mul_f32_e32 v33, v7, v0
	v_mul_f32_e32 v22, v16, v0
	v_mul_f32_e32 v30, v8, v0
	v_mul_f32_e32 v23, v17, v0
	v_mul_f32_e32 v31, v9, v0
	v_mul_f32_e32 v24, v10, v0
	v_mul_f32_e32 v40, v2, v0
	v_mul_f32_e32 v25, v11, v0
	v_mul_f32_e32 v41, v3, v0
	v_mul_f32_e32 v26, v12, v0
	v_mul_f32_e32 v38, v4, v0
	v_mul_f32_e32 v27, v13, v0
	v_mul_f32_e32 v39, v5, v0
	v_mul_f32_e32 v20, v20, v74
	v_mul_f32_e32 v32, v32, v78
	v_mul_f32_e32 v21, v21, v75
	v_mul_f32_e32 v33, v33, v79
	v_mul_f32_e32 v22, v22, v76
	v_mul_f32_e32 v30, v30, v80
	v_mul_f32_e32 v23, v23, v77
	v_mul_f32_e32 v31, v31, v81
	v_mul_f32_e32 v24, v24, v66
	v_mul_f32_e32 v40, v40, v70
	v_mul_f32_e32 v25, v25, v67
	v_mul_f32_e32 v41, v41, v71
	v_mul_f32_e32 v26, v26, v68
	v_mul_f32_e32 v38, v38, v72
	v_mul_f32_e32 v27, v27, v69
	v_mul_f32_e32 v39, v39, v73
	s_cmp_eq_u64 s[6:7], 0
	s_cbranch_scc1 .Lqkv_norope_7
	v_mul_f32_e32 v34, v32, v95
	v_mul_f32_e32 v35, v20, v95
	v_fma_f32 v20, v20, v94, -v34
	v_fma_f32 v32, v32, v94, v35
	v_mul_f32_e32 v34, v33, v97
	v_mul_f32_e32 v35, v21, v97
	v_fma_f32 v21, v21, v96, -v34
	v_fma_f32 v33, v33, v96, v35
	v_mul_f32_e32 v34, v30, v99
	v_mul_f32_e32 v35, v22, v99
	v_fma_f32 v22, v22, v98, -v34
	v_fma_f32 v30, v30, v98, v35
	v_mul_f32_e32 v34, v31, v101
	v_mul_f32_e32 v35, v23, v101
	v_fma_f32 v23, v23, v100, -v34
	v_fma_f32 v31, v31, v100, v35
	v_mul_f32_e32 v34, v40, v87
	v_mul_f32_e32 v35, v24, v87
	v_fma_f32 v24, v24, v86, -v34
	v_fma_f32 v40, v40, v86, v35
	v_mul_f32_e32 v34, v41, v89
	v_mul_f32_e32 v35, v25, v89
	v_fma_f32 v25, v25, v88, -v34
	v_fma_f32 v41, v41, v88, v35
	v_mul_f32_e32 v34, v38, v83
	v_mul_f32_e32 v35, v26, v83
	v_fma_f32 v26, v26, v82, -v34
	v_fma_f32 v38, v38, v82, v35
	v_mul_f32_e32 v34, v39, v85
	v_mul_f32_e32 v35, v27, v85
	v_fma_f32 v27, v27, v84, -v34
	v_fma_f32 v39, v39, v84, v35
